# grid barrier flat release, leaders no longer bump or wait on the per-XCD generation word
# speedup vs baseline: 1.0040x; 1.0040x over previous
; __device__ __forceinline__ unsigned xb_ld(unsigned* p)              { return __hip_atomic_load(p, __ATOMIC_RELAXED, __HIP_MEMORY_SCOPE_AGENT); }
; __device__ __forceinline__ unsigned xb_add(unsigned* p, unsigned v) { return __hip_atomic_fetch_add(p, v, __ATOMIC_RELAXED, __HIP_MEMORY_SCOPE_AGENT); }
; #define XB_SPIN(cond, bar) do { unsigned _sp = 0; while (cond) { __builtin_amdgcn_s_sleep(1); \
;     if ((++_sp & 255u) == 0u) { if (xb_ld(&(bar)[XB_TMO])) break; if (_sp > XB_SPIN_CAP) { atomicAdd(&(bar)[XB_TMO], 1u); break; } } } } while (0)
; __device__ __forceinline__ void xcd_barrier(const XcdBarrier& b) {
;     ...
;             __builtin_amdgcn_fence(__ATOMIC_RELEASE, "agent");
;             asm volatile("s_waitcnt vmcnt(0)" ::: "memory");
;             const unsigned og = xb_add(&bar[XB_TOP], 1u);
;             const unsigned tg = og / nx;
;             if (og + 1u == (tg + 1u) * nx) xb_add(&bar[XB_TOPGEN], 1u);
;             else XB_SPIN(xb_ld(&bar[XB_TOPGEN]) == tg, bar);
;             __builtin_amdgcn_fence(__ATOMIC_ACQUIRE, "agent");
;             xb_add(&bar[XB_XGEN(b.x)], 1u);
;             asm volatile("s_waitcnt vmcnt(0)" ::: "memory");
.LBB0_96:
	s_or_b64 exec, exec, s[38:39]
	buffer_inv sc1
	s_waitcnt vmcnt(0)
